# attention work distribution: per-XCD item queues (4 batch-head pairs per XCD so K/V tiles of a head stay in one XCD L2), static first item, work stealing from the fullest queue at the tail
# speedup vs baseline: 1.0168x; 1.0023x over previous
; __device__ __forceinline__ int get_bid() { int b = blockIdx.x; asm volatile("" : "+s"(b)); return b; }
; __device__ void run_phase(const Params& p, int ph, char* smem) {
;     ...
;         for (int r = 0; r < nr; ++r) {
;             if (l == 0 && quant_first) do_quant(r);
;             const int pos = (r & 1) ? (G - 1 - get_bid()) : get_bid();
;             const int si = r * G + pos;
;             if (si < 2048) attn_item(p, si, smem);
;             if (l == 0 && !quant_first) do_quant(r);
;         }
.LBB0_101:
	s_cmp_eq_u32 s11, 0
	s_cbranch_scc0 .Ltk_dyn
	s_and_b32 s12, s2, 7
	s_lshr_b32 s13, s2, 3
	s_and_b32 s14, s13, 3
	s_lshr_b32 s13, s13, 2
	s_lshl_b32 s15, s13, 5
	s_lshl_b32 s13, s14, 1
	s_add_i32 s13, s13, s12
	s_and_b32 s13, s13, 7
	s_lshl_b32 s14, s14, 3
	s_or_b32 s15, s15, s14
	s_or_b32 s15, s15, s13
	v_mov_b32_e32 v0, 0x9c40
	v_mov_b32_e32 v1, s15
	ds_write_b32 v0, v1
	s_waitcnt lgkmcnt(0)
	s_cmpk_gt_i32 s15, 0x7ff
	s_cbranch_scc0 .LBB0_107
	s_branch .LBB0_104
.Ltk_dyn:
	s_waitcnt lgkmcnt(0)
	s_barrier
	v_cmp_eq_u32_e32 vcc, 0, v126
	s_and_saveexec_b64 s[98:99], vcc
	s_cbranch_execz .Ltk_skip
	v_readlane_b32 s12, v165, 2
	v_readlane_b32 s13, v165, 3
	v_readlane_b32 s15, v167, 36
	s_mul_i32 s15, s15, 0xc00
	s_addk_i32 s15, 0x840
	s_and_b32 s18, s2, 7
	s_lshl_b32 s17, s18, 7
	s_add_i32 s17, s17, s15
	v_mov_b32_e32 v0, s17
	v_mov_b32_e32 v1, 1
	s_nop 2
	global_atomic_add v0, v0, v1, s[12:13] sc0
	s_waitcnt vmcnt(0)
	v_readfirstlane_b32 s14, v0
	s_add_i32 s14, s14, 0x60
	s_cmp_lt_u32 s14, 0x100
	s_cbranch_scc1 .Ltk_have
.Ltk_steal:
	s_mov_b64 exec, 0xff
	v_lshlrev_b32_e32 v0, 7, v130
	v_add_u32_e32 v0, s15, v0
	v_mov_b32_e32 v1, 0
	global_atomic_add v0, v0, v1, s[12:13] sc0
	s_mov_b32 s18, -1
	s_movk_i32 s14, 0xa0
	s_waitcnt vmcnt(0)
	v_readlane_b32 s17, v0, 0
	s_cmp_lt_u32 s17, s14
	s_cselect_b32 s14, s17, s14
	s_cselect_b32 s18, 0, s18
	v_readlane_b32 s17, v0, 1
	s_cmp_lt_u32 s17, s14
	s_cselect_b32 s14, s17, s14
	s_cselect_b32 s18, 1, s18
	v_readlane_b32 s17, v0, 2
	s_cmp_lt_u32 s17, s14
	s_cselect_b32 s14, s17, s14
	s_cselect_b32 s18, 2, s18
	v_readlane_b32 s17, v0, 3
	s_cmp_lt_u32 s17, s14
	s_cselect_b32 s14, s17, s14
	s_cselect_b32 s18, 3, s18
	v_readlane_b32 s17, v0, 4
	s_cmp_lt_u32 s17, s14
	s_cselect_b32 s14, s17, s14
	s_cselect_b32 s18, 4, s18
	v_readlane_b32 s17, v0, 5
	s_cmp_lt_u32 s17, s14
	s_cselect_b32 s14, s17, s14
	s_cselect_b32 s18, 5, s18
	v_readlane_b32 s17, v0, 6
	s_cmp_lt_u32 s17, s14
	s_cselect_b32 s14, s17, s14
	s_cselect_b32 s18, 6, s18
	v_readlane_b32 s17, v0, 7
	s_cmp_lt_u32 s17, s14
	s_cselect_b32 s14, s17, s14
	s_cselect_b32 s18, 7, s18
	s_mov_b64 exec, 1
	s_cmp_lg_u32 s18, -1
	s_cbranch_scc0 .Ltk_none
	s_lshl_b32 s17, s18, 7
	s_add_i32 s17, s17, s15
	v_mov_b32_e32 v0, s17
	v_mov_b32_e32 v1, 1
	global_atomic_add v0, v0, v1, s[12:13] sc0
	s_waitcnt vmcnt(0)
	v_readfirstlane_b32 s14, v0
	s_add_i32 s14, s14, 0x60
	s_cmp_lt_u32 s14, 0x100
	s_cbranch_scc0 .Ltk_steal
.Ltk_have:
	s_and_b32 s16, s14, 3
	s_lshr_b32 s14, s14, 2
	s_lshl_b32 s14, s14, 5
	s_lshl_b32 s17, s16, 1
	s_add_i32 s17, s17, s18
	s_and_b32 s17, s17, 7
	s_lshl_b32 s16, s16, 3
	s_or_b32 s14, s14, s16
	s_or_b32 s14, s14, s17
	v_mov_b32_e32 v0, s14
	v_mov_b32_e32 v1, 0x9c40
	ds_write_b32 v1, v0
	s_branch .Ltk_skip
.Ltk_none:
	v_mov_b32_e32 v0, 0x1000
	v_mov_b32_e32 v1, 0x9c40
	ds_write_b32 v1, v0
